# attention O stores sc1 nt
# baseline (speedup 1.0000x reference)
.LBB0_303:
	s_cmpk_gt_u32 s65, 0xff
	s_waitcnt lgkmcnt(0)
	s_barrier
	s_cbranch_scc1 .LBB0_275
	s_mulk_i32 s64, 0x2200
	s_add_i32 s34, s64, 0
	s_add_i32 s34, s34, 0x10000
	ds_read2st64_b32 v[130:131], v71 offset1:1
	ds_read2st64_b32 v[132:133], v71 offset0:2 offset1:3
	ds_read2st64_b32 v[134:135], v71 offset0:4 offset1:5
	ds_read2st64_b32 v[136:137], v71 offset0:6 offset1:7
	ds_read2st64_b32 v[138:139], v71 offset0:8 offset1:9
	ds_read2st64_b32 v[140:141], v71 offset0:10 offset1:11
	ds_read2st64_b32 v[142:143], v71 offset0:12 offset1:13
	ds_read2st64_b32 v[144:145], v71 offset0:14 offset1:15
	ds_read2st64_b32 v[146:147], v71 offset0:16 offset1:17
	ds_read2st64_b32 v[148:149], v71 offset0:18 offset1:19
	ds_read2st64_b32 v[150:151], v71 offset0:20 offset1:21
	ds_read2st64_b32 v[172:173], v71 offset0:22 offset1:23
	ds_read2st64_b32 v[174:175], v71 offset0:24 offset1:25
	ds_read2st64_b32 v[176:177], v71 offset0:26 offset1:27
	ds_read2st64_b32 v[178:179], v71 offset0:28 offset1:29
	ds_read2st64_b32 v[180:181], v71 offset0:30 offset1:31
	ds_read2st64_b32 v[182:183], v71 offset0:32 offset1:33
	ds_read2st64_b32 v[184:185], v71 offset0:34 offset1:35
	ds_read2st64_b32 v[186:187], v71 offset0:36 offset1:37
	ds_read2st64_b32 v[188:189], v71 offset0:38 offset1:39
	ds_read2st64_b32 v[190:191], v71 offset0:40 offset1:41
	ds_read2st64_b32 v[192:193], v71 offset0:42 offset1:43
	ds_read2st64_b32 v[194:195], v71 offset0:44 offset1:45
	ds_read2st64_b32 v[196:197], v71 offset0:46 offset1:47
	ds_read2st64_b32 v[198:199], v71 offset0:48 offset1:49
	ds_read2st64_b32 v[200:201], v71 offset0:50 offset1:51
	ds_read2st64_b32 v[202:203], v71 offset0:52 offset1:53
	ds_read2st64_b32 v[204:205], v71 offset0:54 offset1:55
	ds_read2st64_b32 v[206:207], v71 offset0:56 offset1:57
	ds_read2st64_b32 v[208:209], v71 offset0:58 offset1:59
	ds_read2st64_b32 v[210:211], v71 offset0:60 offset1:61
	ds_read2st64_b32 v[212:213], v71 offset0:62 offset1:63
	s_waitcnt lgkmcnt(15)
	v_sub_f32_e32 v60, v72, v130
	v_sub_f32_e32 v55, v0, v131
	v_sub_f32_e32 v52, v73, v132
	v_sub_f32_e32 v47, v74, v133
	v_sub_f32_e32 v44, v3, v134
	v_sub_f32_e32 v39, v36, v135
	v_sub_f32_e32 v28, v23, v138
	v_sub_f32_e32 v23, v38, v139
	v_sub_f32_e32 v36, v20, v136
	v_sub_f32_e32 v31, v6, v137
	v_sub_f32_e32 v20, v41, v140
	v_sub_f32_e32 v15, v26, v141
	v_sub_f32_e32 v12, v54, v142
	v_sub_f32_e32 v6, v77, v143
	v_sub_f32_e32 v3, v57, v144
	v_sub_f32_e32 v0, v14, v145
	v_sub_f32_e32 v62, v68, v146
	v_sub_f32_e32 v57, v49, v147
	v_sub_f32_e32 v54, v1, v148
	v_sub_f32_e32 v49, v18, v149
	v_sub_f32_e32 v46, v34, v150
	v_sub_f32_e32 v41, v51, v151
	v_sub_f32_e32 v38, v5, v172
	v_sub_f32_e32 v34, v22, v173
	v_sub_f32_e32 v30, v40, v174
	v_sub_f32_e32 v26, v56, v175
	v_sub_f32_e32 v22, v75, v176
	v_sub_f32_e32 v18, v10, v177
	v_sub_f32_e32 v14, v27, v178
	v_sub_f32_e32 v10, v59, v179
	v_sub_f32_e32 v5, v43, v180
	v_sub_f32_e32 v1, v76, v181
	v_sub_f32_e32 v74, v16, v182
	v_sub_f32_e32 v59, v32, v183
	s_waitcnt lgkmcnt(14)
	v_sub_f32_e32 v56, v48, v184
	v_sub_f32_e32 v51, v2, v185
	s_waitcnt lgkmcnt(13)
	v_sub_f32_e32 v48, v19, v186
	v_sub_f32_e32 v43, v53, v187
	s_waitcnt lgkmcnt(12)
	v_sub_f32_e32 v40, v35, v188
	v_sub_f32_e32 v35, v69, v189
	s_waitcnt lgkmcnt(11)
	v_sub_f32_e32 v32, v7, v190
	v_sub_f32_e32 v27, v24, v191
	s_waitcnt lgkmcnt(10)
	v_sub_f32_e32 v24, v42, v192
	v_sub_f32_e32 v19, v58, v193
	s_waitcnt lgkmcnt(9)
	v_sub_f32_e32 v16, v11, v194
	v_sub_f32_e32 v11, v29, v195
	s_waitcnt lgkmcnt(8)
	v_sub_f32_e32 v7, v45, v196
	v_sub_f32_e32 v2, v61, v197
	s_waitcnt lgkmcnt(7)
	v_sub_f32_e32 v72, v64, v198
	v_sub_f32_e32 v61, v17, v199
	s_waitcnt lgkmcnt(6)
	v_sub_f32_e32 v58, v33, v200
	v_sub_f32_e32 v53, v50, v201
	s_waitcnt lgkmcnt(5)
	v_sub_f32_e32 v50, v4, v202
	v_sub_f32_e32 v45, v21, v203
	s_waitcnt lgkmcnt(4)
	v_sub_f32_e32 v42, v37, v204
	v_sub_f32_e32 v37, v65, v205
	s_waitcnt lgkmcnt(3)
	v_sub_f32_e32 v33, v8, v206
	v_sub_f32_e32 v29, v9, v207
	s_waitcnt lgkmcnt(2)
	v_sub_f32_e32 v25, v25, v208
	v_sub_f32_e32 v21, v66, v209
	s_waitcnt lgkmcnt(0)
	v_sub_f32_e32 v4, v63, v213
	v_sub_f32_e32 v13, v13, v211
	v_sub_f32_e32 v9, v70, v212
	v_sub_f32_e32 v17, v67, v210
	s_waitcnt lgkmcnt(0)
	v_mul_f32_e32 v130, v62, v62
	v_fmac_f32_e32 v130, v60, v60
	v_fmac_f32_e32 v130, v74, v74
	v_fmac_f32_e32 v130, v72, v72
	v_mul_f32_e32 v131, v57, v57
	v_fmac_f32_e32 v131, v55, v55
	v_fmac_f32_e32 v131, v59, v59
	v_fmac_f32_e32 v131, v61, v61
	v_mul_f32_e32 v132, v54, v54
	v_fmac_f32_e32 v132, v52, v52
	v_fmac_f32_e32 v132, v56, v56
	v_fmac_f32_e32 v132, v58, v58
	v_mul_f32_e32 v133, v49, v49
	v_fmac_f32_e32 v133, v47, v47
	v_fmac_f32_e32 v133, v51, v51
	v_fmac_f32_e32 v133, v53, v53
	v_mul_f32_e32 v134, v46, v46
	v_fmac_f32_e32 v134, v44, v44
	v_fmac_f32_e32 v134, v48, v48
	v_fmac_f32_e32 v134, v50, v50
	v_mul_f32_e32 v135, v41, v41
	v_fmac_f32_e32 v135, v39, v39
	v_fmac_f32_e32 v135, v43, v43
	v_fmac_f32_e32 v135, v45, v45
	v_mul_f32_e32 v136, v38, v38
	v_fmac_f32_e32 v136, v36, v36
	v_fmac_f32_e32 v136, v40, v40
	v_fmac_f32_e32 v136, v42, v42
	v_mul_f32_e32 v137, v34, v34
	v_fmac_f32_e32 v137, v31, v31
	v_fmac_f32_e32 v137, v35, v35
	v_fmac_f32_e32 v137, v37, v37
	v_mul_f32_e32 v138, v30, v30
	v_fmac_f32_e32 v138, v28, v28
	v_fmac_f32_e32 v138, v32, v32
	v_fmac_f32_e32 v138, v33, v33
	v_mul_f32_e32 v139, v26, v26
	v_fmac_f32_e32 v139, v23, v23
	v_fmac_f32_e32 v139, v27, v27
	v_fmac_f32_e32 v139, v29, v29
	v_mul_f32_e32 v140, v22, v22
	v_fmac_f32_e32 v140, v20, v20
	v_fmac_f32_e32 v140, v24, v24
	v_fmac_f32_e32 v140, v25, v25
	v_mul_f32_e32 v141, v18, v18
	v_fmac_f32_e32 v141, v15, v15
	v_fmac_f32_e32 v141, v19, v19
	v_fmac_f32_e32 v141, v21, v21
	v_mul_f32_e32 v142, v14, v14
	v_fmac_f32_e32 v142, v12, v12
	v_fmac_f32_e32 v142, v16, v16
	v_fmac_f32_e32 v142, v17, v17
	v_mul_f32_e32 v143, v10, v10
	v_fmac_f32_e32 v143, v6, v6
	v_fmac_f32_e32 v143, v11, v11
	v_fmac_f32_e32 v143, v13, v13
	v_mul_f32_e32 v144, v5, v5
	v_fmac_f32_e32 v144, v3, v3
	v_fmac_f32_e32 v144, v7, v7
	v_fmac_f32_e32 v144, v9, v9
	v_mul_f32_e32 v145, v1, v1
	v_fmac_f32_e32 v145, v0, v0
	v_fmac_f32_e32 v145, v2, v2
	v_fmac_f32_e32 v145, v4, v4
	ds_bpermute_b32 v146, v161, v130
	ds_bpermute_b32 v147, v161, v131
	ds_bpermute_b32 v148, v161, v132
	ds_bpermute_b32 v149, v161, v133
	ds_bpermute_b32 v150, v161, v134
	ds_bpermute_b32 v151, v161, v135
	ds_bpermute_b32 v172, v161, v136
	ds_bpermute_b32 v173, v161, v137
	ds_bpermute_b32 v174, v161, v138
	ds_bpermute_b32 v175, v161, v139
	ds_bpermute_b32 v176, v161, v140
	ds_bpermute_b32 v177, v161, v141
	ds_bpermute_b32 v178, v161, v142
	ds_bpermute_b32 v179, v161, v143
	ds_bpermute_b32 v180, v161, v144
	ds_bpermute_b32 v181, v161, v145
	s_waitcnt lgkmcnt(15)
	v_add_f32_e32 v130, v130, v146
	s_waitcnt lgkmcnt(14)
	v_add_f32_e32 v131, v131, v147
	s_waitcnt lgkmcnt(13)
	v_add_f32_e32 v132, v132, v148
	s_waitcnt lgkmcnt(12)
	v_add_f32_e32 v133, v133, v149
	s_waitcnt lgkmcnt(11)
	v_add_f32_e32 v134, v134, v150
	s_waitcnt lgkmcnt(10)
	v_add_f32_e32 v135, v135, v151
	s_waitcnt lgkmcnt(9)
	v_add_f32_e32 v136, v136, v172
	s_waitcnt lgkmcnt(8)
	v_add_f32_e32 v137, v137, v173
	s_waitcnt lgkmcnt(7)
	v_add_f32_e32 v138, v138, v174
	s_waitcnt lgkmcnt(6)
	v_add_f32_e32 v139, v139, v175
	s_waitcnt lgkmcnt(5)
	v_add_f32_e32 v140, v140, v176
	s_waitcnt lgkmcnt(4)
	v_add_f32_e32 v141, v141, v177
	s_waitcnt lgkmcnt(3)
	v_add_f32_e32 v142, v142, v178
	s_waitcnt lgkmcnt(2)
	v_add_f32_e32 v143, v143, v179
	s_waitcnt lgkmcnt(1)
	v_add_f32_e32 v144, v144, v180
	s_waitcnt lgkmcnt(0)
	v_add_f32_e32 v145, v145, v181
	ds_bpermute_b32 v146, v162, v130
	ds_bpermute_b32 v147, v162, v131
	ds_bpermute_b32 v148, v162, v132
	ds_bpermute_b32 v149, v162, v133
	ds_bpermute_b32 v150, v162, v134
	ds_bpermute_b32 v151, v162, v135
	ds_bpermute_b32 v172, v162, v136
	ds_bpermute_b32 v173, v162, v137
	ds_bpermute_b32 v174, v162, v138
	ds_bpermute_b32 v175, v162, v139
	ds_bpermute_b32 v176, v162, v140
	ds_bpermute_b32 v177, v162, v141
	ds_bpermute_b32 v178, v162, v142
	ds_bpermute_b32 v179, v162, v143
	ds_bpermute_b32 v180, v162, v144
	ds_bpermute_b32 v181, v162, v145
	s_waitcnt lgkmcnt(15)
	v_add_f32_e32 v130, v130, v146
	s_waitcnt lgkmcnt(14)
	v_add_f32_e32 v131, v131, v147
	s_waitcnt lgkmcnt(13)
	v_add_f32_e32 v132, v132, v148
	s_waitcnt lgkmcnt(12)
	v_add_f32_e32 v133, v133, v149
	s_waitcnt lgkmcnt(11)
	v_add_f32_e32 v134, v134, v150
	s_waitcnt lgkmcnt(10)
	v_add_f32_e32 v135, v135, v151
	s_waitcnt lgkmcnt(9)
	v_add_f32_e32 v136, v136, v172
	s_waitcnt lgkmcnt(8)
	v_add_f32_e32 v137, v137, v173
	s_waitcnt lgkmcnt(7)
	v_add_f32_e32 v138, v138, v174
	s_waitcnt lgkmcnt(6)
	v_add_f32_e32 v139, v139, v175
	s_waitcnt lgkmcnt(5)
	v_add_f32_e32 v140, v140, v176
	s_waitcnt lgkmcnt(4)
	v_add_f32_e32 v141, v141, v177
	s_waitcnt lgkmcnt(3)
	v_add_f32_e32 v142, v142, v178
	s_waitcnt lgkmcnt(2)
	v_add_f32_e32 v143, v143, v179
	s_waitcnt lgkmcnt(1)
	v_add_f32_e32 v144, v144, v180
	s_waitcnt lgkmcnt(0)
	v_add_f32_e32 v145, v145, v181
	ds_bpermute_b32 v146, v163, v130
	ds_bpermute_b32 v147, v163, v131
	ds_bpermute_b32 v148, v163, v132
	ds_bpermute_b32 v149, v163, v133
	ds_bpermute_b32 v150, v163, v134
	ds_bpermute_b32 v151, v163, v135
	ds_bpermute_b32 v172, v163, v136
	ds_bpermute_b32 v173, v163, v137
	ds_bpermute_b32 v174, v163, v138
	ds_bpermute_b32 v175, v163, v139
	ds_bpermute_b32 v176, v163, v140
	ds_bpermute_b32 v177, v163, v141
	ds_bpermute_b32 v178, v163, v142
	ds_bpermute_b32 v179, v163, v143
	ds_bpermute_b32 v180, v163, v144
	ds_bpermute_b32 v181, v163, v145
	s_waitcnt lgkmcnt(15)
	v_add_f32_e32 v130, v130, v146
	s_waitcnt lgkmcnt(14)
	v_add_f32_e32 v131, v131, v147
	s_waitcnt lgkmcnt(13)
	v_add_f32_e32 v132, v132, v148
	s_waitcnt lgkmcnt(12)
	v_add_f32_e32 v133, v133, v149
	s_waitcnt lgkmcnt(11)
	v_add_f32_e32 v134, v134, v150
	s_waitcnt lgkmcnt(10)
	v_add_f32_e32 v135, v135, v151
	s_waitcnt lgkmcnt(9)
	v_add_f32_e32 v136, v136, v172
	s_waitcnt lgkmcnt(8)
	v_add_f32_e32 v137, v137, v173
	s_waitcnt lgkmcnt(7)
	v_add_f32_e32 v138, v138, v174
	s_waitcnt lgkmcnt(6)
	v_add_f32_e32 v139, v139, v175
	s_waitcnt lgkmcnt(5)
	v_add_f32_e32 v140, v140, v176
	s_waitcnt lgkmcnt(4)
	v_add_f32_e32 v141, v141, v177
	s_waitcnt lgkmcnt(3)
	v_add_f32_e32 v142, v142, v178
	s_waitcnt lgkmcnt(2)
	v_add_f32_e32 v143, v143, v179
	s_waitcnt lgkmcnt(1)
	v_add_f32_e32 v144, v144, v180
	s_waitcnt lgkmcnt(0)
	v_add_f32_e32 v145, v145, v181
	ds_bpermute_b32 v146, v164, v130
	ds_bpermute_b32 v147, v164, v131
	ds_bpermute_b32 v148, v164, v132
	ds_bpermute_b32 v149, v164, v133
	ds_bpermute_b32 v150, v164, v134
	ds_bpermute_b32 v151, v164, v135
	ds_bpermute_b32 v172, v164, v136
	ds_bpermute_b32 v173, v164, v137
	ds_bpermute_b32 v174, v164, v138
	ds_bpermute_b32 v175, v164, v139
	ds_bpermute_b32 v176, v164, v140
	ds_bpermute_b32 v177, v164, v141
	ds_bpermute_b32 v178, v164, v142
	ds_bpermute_b32 v179, v164, v143
	ds_bpermute_b32 v180, v164, v144
	ds_bpermute_b32 v181, v164, v145
	s_waitcnt lgkmcnt(15)
	v_add_f32_e32 v130, v130, v146
	s_waitcnt lgkmcnt(14)
	v_add_f32_e32 v131, v131, v147
	s_waitcnt lgkmcnt(13)
	v_add_f32_e32 v132, v132, v148
	s_waitcnt lgkmcnt(12)
	v_add_f32_e32 v133, v133, v149
	s_waitcnt lgkmcnt(11)
	v_add_f32_e32 v134, v134, v150
	s_waitcnt lgkmcnt(10)
	v_add_f32_e32 v135, v135, v151
	s_waitcnt lgkmcnt(9)
	v_add_f32_e32 v136, v136, v172
	s_waitcnt lgkmcnt(8)
	v_add_f32_e32 v137, v137, v173
	s_waitcnt lgkmcnt(7)
	v_add_f32_e32 v138, v138, v174
	s_waitcnt lgkmcnt(6)
	v_add_f32_e32 v139, v139, v175
	s_waitcnt lgkmcnt(5)
	v_add_f32_e32 v140, v140, v176
	s_waitcnt lgkmcnt(4)
	v_add_f32_e32 v141, v141, v177
	s_waitcnt lgkmcnt(3)
	v_add_f32_e32 v142, v142, v178
	s_waitcnt lgkmcnt(2)
	v_add_f32_e32 v143, v143, v179
	s_waitcnt lgkmcnt(1)
	v_add_f32_e32 v144, v144, v180
	s_waitcnt lgkmcnt(0)
	v_add_f32_e32 v145, v145, v181
	ds_bpermute_b32 v146, v165, v130
	ds_bpermute_b32 v147, v165, v131
	ds_bpermute_b32 v148, v165, v132
	ds_bpermute_b32 v149, v165, v133
	ds_bpermute_b32 v150, v165, v134
	ds_bpermute_b32 v151, v165, v135
	ds_bpermute_b32 v172, v165, v136
	ds_bpermute_b32 v173, v165, v137
	ds_bpermute_b32 v174, v165, v138
	ds_bpermute_b32 v175, v165, v139
	ds_bpermute_b32 v176, v165, v140
	ds_bpermute_b32 v177, v165, v141
	ds_bpermute_b32 v178, v165, v142
	ds_bpermute_b32 v179, v165, v143
	ds_bpermute_b32 v180, v165, v144
	ds_bpermute_b32 v181, v165, v145
	s_waitcnt lgkmcnt(15)
	v_add_f32_e32 v130, v130, v146
	s_waitcnt lgkmcnt(14)
	v_add_f32_e32 v131, v131, v147
	s_waitcnt lgkmcnt(13)
	v_add_f32_e32 v132, v132, v148
	s_waitcnt lgkmcnt(12)
	v_add_f32_e32 v133, v133, v149
	s_waitcnt lgkmcnt(11)
	v_add_f32_e32 v134, v134, v150
	s_waitcnt lgkmcnt(10)
	v_add_f32_e32 v135, v135, v151
	s_waitcnt lgkmcnt(9)
	v_add_f32_e32 v136, v136, v172
	s_waitcnt lgkmcnt(8)
	v_add_f32_e32 v137, v137, v173
	s_waitcnt lgkmcnt(7)
	v_add_f32_e32 v138, v138, v174
	s_waitcnt lgkmcnt(6)
	v_add_f32_e32 v139, v139, v175
	s_waitcnt lgkmcnt(5)
	v_add_f32_e32 v140, v140, v176
	s_waitcnt lgkmcnt(4)
	v_add_f32_e32 v141, v141, v177
	s_waitcnt lgkmcnt(3)
	v_add_f32_e32 v142, v142, v178
	s_waitcnt lgkmcnt(2)
	v_add_f32_e32 v143, v143, v179
	s_waitcnt lgkmcnt(1)
	v_add_f32_e32 v144, v144, v180
	s_waitcnt lgkmcnt(0)
	v_add_f32_e32 v145, v145, v181
	v_fmamk_f32 v130, v130, 0x3c000000, v153
	v_fmamk_f32 v131, v131, 0x3c000000, v153
	v_fmamk_f32 v132, v132, 0x3c000000, v153
	v_fmamk_f32 v133, v133, 0x3c000000, v153
	v_fmamk_f32 v134, v134, 0x3c000000, v153
	v_fmamk_f32 v135, v135, 0x3c000000, v153
	v_fmamk_f32 v136, v136, 0x3c000000, v153
	v_fmamk_f32 v137, v137, 0x3c000000, v153
	v_fmamk_f32 v138, v138, 0x3c000000, v153
	v_fmamk_f32 v139, v139, 0x3c000000, v153
	v_fmamk_f32 v140, v140, 0x3c000000, v153
	v_fmamk_f32 v141, v141, 0x3c000000, v153
	v_fmamk_f32 v142, v142, 0x3c000000, v153
	v_fmamk_f32 v143, v143, 0x3c000000, v153
	v_fmamk_f32 v144, v144, 0x3c000000, v153
	v_fmamk_f32 v145, v145, 0x3c000000, v153
	v_rsq_f32_e32 v130, v130
	v_rsq_f32_e32 v131, v131
	v_rsq_f32_e32 v132, v132
	v_rsq_f32_e32 v133, v133
	v_rsq_f32_e32 v134, v134
	v_rsq_f32_e32 v135, v135
	v_rsq_f32_e32 v136, v136
	v_rsq_f32_e32 v137, v137
	v_rsq_f32_e32 v138, v138
	v_rsq_f32_e32 v139, v139
	v_rsq_f32_e32 v140, v140
	v_rsq_f32_e32 v141, v141
	v_rsq_f32_e32 v142, v142
	v_rsq_f32_e32 v143, v143
	v_rsq_f32_e32 v144, v144
	v_rsq_f32_e32 v145, v145
	v_lshlrev_b32_e32 v190, 1, v171
	v_mul_u32_u24_e32 v191, 0x440, v170
	v_add3_u32 v190, s34, v190, v191
	v_mul_f32_e32 v182, v60, v130
	v_bfe_u32 v186, v182, 16, 1
	v_add3_u32 v182, v182, v186, s81
	ds_write_b16_d16_hi v190, v182
	v_mul_f32_e32 v183, v62, v130
	v_bfe_u32 v187, v183, 16, 1
	v_add3_u32 v183, v183, v187, s81
	ds_write_b16_d16_hi v190, v183 offset:64
	v_mul_f32_e32 v184, v74, v130
	v_bfe_u32 v188, v184, 16, 1
	v_add3_u32 v184, v184, v188, s81
	ds_write_b16_d16_hi v190, v184 offset:128
	v_mul_f32_e32 v185, v72, v130
	v_bfe_u32 v189, v185, 16, 1
	v_add3_u32 v185, v185, v189, s81
	ds_write_b16_d16_hi v190, v185 offset:192
	v_mul_f32_e32 v182, v55, v131
	v_bfe_u32 v186, v182, 16, 1
	v_add3_u32 v182, v182, v186, s81
	ds_write_b16_d16_hi v190, v182 offset:272
	v_mul_f32_e32 v183, v57, v131
	v_bfe_u32 v187, v183, 16, 1
	v_add3_u32 v183, v183, v187, s81
	ds_write_b16_d16_hi v190, v183 offset:336
	v_mul_f32_e32 v184, v59, v131
	v_bfe_u32 v188, v184, 16, 1
	v_add3_u32 v184, v184, v188, s81
	ds_write_b16_d16_hi v190, v184 offset:400
	v_mul_f32_e32 v185, v61, v131
	v_bfe_u32 v189, v185, 16, 1
	v_add3_u32 v185, v185, v189, s81
	ds_write_b16_d16_hi v190, v185 offset:464
	v_mul_f32_e32 v182, v52, v132
	v_bfe_u32 v186, v182, 16, 1
	v_add3_u32 v182, v182, v186, s81
	ds_write_b16_d16_hi v190, v182 offset:544
	v_mul_f32_e32 v183, v54, v132
	v_bfe_u32 v187, v183, 16, 1
	v_add3_u32 v183, v183, v187, s81
	ds_write_b16_d16_hi v190, v183 offset:608
	v_mul_f32_e32 v184, v56, v132
	v_bfe_u32 v188, v184, 16, 1
	v_add3_u32 v184, v184, v188, s81
	ds_write_b16_d16_hi v190, v184 offset:672
	v_mul_f32_e32 v185, v58, v132
	v_bfe_u32 v189, v185, 16, 1
	v_add3_u32 v185, v185, v189, s81
	ds_write_b16_d16_hi v190, v185 offset:736
	v_mul_f32_e32 v182, v47, v133
	v_bfe_u32 v186, v182, 16, 1
	v_add3_u32 v182, v182, v186, s81
	ds_write_b16_d16_hi v190, v182 offset:816
	v_mul_f32_e32 v183, v49, v133
	v_bfe_u32 v187, v183, 16, 1
	v_add3_u32 v183, v183, v187, s81
	ds_write_b16_d16_hi v190, v183 offset:880
	v_mul_f32_e32 v184, v51, v133
	v_bfe_u32 v188, v184, 16, 1
	v_add3_u32 v184, v184, v188, s81
	ds_write_b16_d16_hi v190, v184 offset:944
	v_mul_f32_e32 v185, v53, v133
	v_bfe_u32 v189, v185, 16, 1
	v_add3_u32 v185, v185, v189, s81
	ds_write_b16_d16_hi v190, v185 offset:1008
	v_mul_f32_e32 v182, v44, v134
	v_bfe_u32 v186, v182, 16, 1
	v_add3_u32 v182, v182, v186, s81
	ds_write_b16_d16_hi v190, v182 offset:2176
	v_mul_f32_e32 v183, v46, v134
	v_bfe_u32 v187, v183, 16, 1
	v_add3_u32 v183, v183, v187, s81
	ds_write_b16_d16_hi v190, v183 offset:2240
	v_mul_f32_e32 v184, v48, v134
	v_bfe_u32 v188, v184, 16, 1
	v_add3_u32 v184, v184, v188, s81
	ds_write_b16_d16_hi v190, v184 offset:2304
	v_mul_f32_e32 v185, v50, v134
	v_bfe_u32 v189, v185, 16, 1
	v_add3_u32 v185, v185, v189, s81
	ds_write_b16_d16_hi v190, v185 offset:2368
	v_mul_f32_e32 v182, v39, v135
	v_bfe_u32 v186, v182, 16, 1
	v_add3_u32 v182, v182, v186, s81
	ds_write_b16_d16_hi v190, v182 offset:2448
	v_mul_f32_e32 v183, v41, v135
	v_bfe_u32 v187, v183, 16, 1
	v_add3_u32 v183, v183, v187, s81
	ds_write_b16_d16_hi v190, v183 offset:2512
	v_mul_f32_e32 v184, v43, v135
	v_bfe_u32 v188, v184, 16, 1
	v_add3_u32 v184, v184, v188, s81
	ds_write_b16_d16_hi v190, v184 offset:2576
	v_mul_f32_e32 v185, v45, v135
	v_bfe_u32 v189, v185, 16, 1
	v_add3_u32 v185, v185, v189, s81
	ds_write_b16_d16_hi v190, v185 offset:2640
	v_mul_f32_e32 v182, v36, v136
	v_bfe_u32 v186, v182, 16, 1
	v_add3_u32 v182, v182, v186, s81
	ds_write_b16_d16_hi v190, v182 offset:2720
	v_mul_f32_e32 v183, v38, v136
	v_bfe_u32 v187, v183, 16, 1
	v_add3_u32 v183, v183, v187, s81
	ds_write_b16_d16_hi v190, v183 offset:2784
	v_mul_f32_e32 v184, v40, v136
	v_bfe_u32 v188, v184, 16, 1
	v_add3_u32 v184, v184, v188, s81
	ds_write_b16_d16_hi v190, v184 offset:2848
	v_mul_f32_e32 v185, v42, v136
	v_bfe_u32 v189, v185, 16, 1
	v_add3_u32 v185, v185, v189, s81
	ds_write_b16_d16_hi v190, v185 offset:2912
	v_mul_f32_e32 v182, v31, v137
	v_bfe_u32 v186, v182, 16, 1
	v_add3_u32 v182, v182, v186, s81
	ds_write_b16_d16_hi v190, v182 offset:2992
	v_mul_f32_e32 v183, v34, v137
	v_bfe_u32 v187, v183, 16, 1
	v_add3_u32 v183, v183, v187, s81
	ds_write_b16_d16_hi v190, v183 offset:3056
	v_mul_f32_e32 v184, v35, v137
	v_bfe_u32 v188, v184, 16, 1
	v_add3_u32 v184, v184, v188, s81
	ds_write_b16_d16_hi v190, v184 offset:3120
	v_mul_f32_e32 v185, v37, v137
	v_bfe_u32 v189, v185, 16, 1
	v_add3_u32 v185, v185, v189, s81
	ds_write_b16_d16_hi v190, v185 offset:3184
	v_mul_f32_e32 v182, v28, v138
	v_bfe_u32 v186, v182, 16, 1
	v_add3_u32 v182, v182, v186, s81
	ds_write_b16_d16_hi v190, v182 offset:4352
	v_mul_f32_e32 v183, v30, v138
	v_bfe_u32 v187, v183, 16, 1
	v_add3_u32 v183, v183, v187, s81
	ds_write_b16_d16_hi v190, v183 offset:4416
	v_mul_f32_e32 v184, v32, v138
	v_bfe_u32 v188, v184, 16, 1
	v_add3_u32 v184, v184, v188, s81
	ds_write_b16_d16_hi v190, v184 offset:4480
	v_mul_f32_e32 v185, v33, v138
	v_bfe_u32 v189, v185, 16, 1
	v_add3_u32 v185, v185, v189, s81
	ds_write_b16_d16_hi v190, v185 offset:4544
	v_mul_f32_e32 v182, v23, v139
	v_bfe_u32 v186, v182, 16, 1
	v_add3_u32 v182, v182, v186, s81
	ds_write_b16_d16_hi v190, v182 offset:4624
	v_mul_f32_e32 v183, v26, v139
	v_bfe_u32 v187, v183, 16, 1
	v_add3_u32 v183, v183, v187, s81
	ds_write_b16_d16_hi v190, v183 offset:4688
	v_mul_f32_e32 v184, v27, v139
	v_bfe_u32 v188, v184, 16, 1
	v_add3_u32 v184, v184, v188, s81
	ds_write_b16_d16_hi v190, v184 offset:4752
	v_mul_f32_e32 v185, v29, v139
	v_bfe_u32 v189, v185, 16, 1
	v_add3_u32 v185, v185, v189, s81
	ds_write_b16_d16_hi v190, v185 offset:4816
	v_mul_f32_e32 v182, v20, v140
	v_bfe_u32 v186, v182, 16, 1
	v_add3_u32 v182, v182, v186, s81
	ds_write_b16_d16_hi v190, v182 offset:4896
	v_mul_f32_e32 v183, v22, v140
	v_bfe_u32 v187, v183, 16, 1
	v_add3_u32 v183, v183, v187, s81
	ds_write_b16_d16_hi v190, v183 offset:4960
	v_mul_f32_e32 v184, v24, v140
	v_bfe_u32 v188, v184, 16, 1
	v_add3_u32 v184, v184, v188, s81
	ds_write_b16_d16_hi v190, v184 offset:5024
	v_mul_f32_e32 v185, v25, v140
	v_bfe_u32 v189, v185, 16, 1
	v_add3_u32 v185, v185, v189, s81
	ds_write_b16_d16_hi v190, v185 offset:5088
	v_mul_f32_e32 v182, v15, v141
	v_bfe_u32 v186, v182, 16, 1
	v_add3_u32 v182, v182, v186, s81
	ds_write_b16_d16_hi v190, v182 offset:5168
	v_mul_f32_e32 v183, v18, v141
	v_bfe_u32 v187, v183, 16, 1
	v_add3_u32 v183, v183, v187, s81
	ds_write_b16_d16_hi v190, v183 offset:5232
	v_mul_f32_e32 v184, v19, v141
	v_bfe_u32 v188, v184, 16, 1
	v_add3_u32 v184, v184, v188, s81
	ds_write_b16_d16_hi v190, v184 offset:5296
	v_mul_f32_e32 v185, v21, v141
	v_bfe_u32 v189, v185, 16, 1
	v_add3_u32 v185, v185, v189, s81
	ds_write_b16_d16_hi v190, v185 offset:5360
	v_mul_f32_e32 v182, v12, v142
	v_bfe_u32 v186, v182, 16, 1
	v_add3_u32 v182, v182, v186, s81
	ds_write_b16_d16_hi v190, v182 offset:6528
	v_mul_f32_e32 v183, v14, v142
	v_bfe_u32 v187, v183, 16, 1
	v_add3_u32 v183, v183, v187, s81
	ds_write_b16_d16_hi v190, v183 offset:6592
	v_mul_f32_e32 v184, v16, v142
	v_bfe_u32 v188, v184, 16, 1
	v_add3_u32 v184, v184, v188, s81
	ds_write_b16_d16_hi v190, v184 offset:6656
	v_mul_f32_e32 v185, v17, v142
	v_bfe_u32 v189, v185, 16, 1
	v_add3_u32 v185, v185, v189, s81
	ds_write_b16_d16_hi v190, v185 offset:6720
	v_mul_f32_e32 v182, v6, v143
	v_bfe_u32 v186, v182, 16, 1
	v_add3_u32 v182, v182, v186, s81
	ds_write_b16_d16_hi v190, v182 offset:6800
	v_mul_f32_e32 v183, v10, v143
	v_bfe_u32 v187, v183, 16, 1
	v_add3_u32 v183, v183, v187, s81
	ds_write_b16_d16_hi v190, v183 offset:6864
	v_mul_f32_e32 v184, v11, v143
	v_bfe_u32 v188, v184, 16, 1
	v_add3_u32 v184, v184, v188, s81
	ds_write_b16_d16_hi v190, v184 offset:6928
	v_mul_f32_e32 v185, v13, v143
	v_bfe_u32 v189, v185, 16, 1
	v_add3_u32 v185, v185, v189, s81
	ds_write_b16_d16_hi v190, v185 offset:6992
	v_mul_f32_e32 v182, v3, v144
	v_bfe_u32 v186, v182, 16, 1
	v_add3_u32 v182, v182, v186, s81
	ds_write_b16_d16_hi v190, v182 offset:7072
	v_mul_f32_e32 v183, v5, v144
	v_bfe_u32 v187, v183, 16, 1
	v_add3_u32 v183, v183, v187, s81
	ds_write_b16_d16_hi v190, v183 offset:7136
	v_mul_f32_e32 v184, v7, v144
	v_bfe_u32 v188, v184, 16, 1
	v_add3_u32 v184, v184, v188, s81
	ds_write_b16_d16_hi v190, v184 offset:7200
	v_mul_f32_e32 v185, v9, v144
	v_bfe_u32 v189, v185, 16, 1
	v_add3_u32 v185, v185, v189, s81
	ds_write_b16_d16_hi v190, v185 offset:7264
	v_mul_f32_e32 v182, v0, v145
	v_bfe_u32 v186, v182, 16, 1
	v_add3_u32 v182, v182, v186, s81
	ds_write_b16_d16_hi v190, v182 offset:7344
	v_mul_f32_e32 v183, v1, v145
	v_bfe_u32 v187, v183, 16, 1
	v_add3_u32 v183, v183, v187, s81
	ds_write_b16_d16_hi v190, v183 offset:7408
	v_mul_f32_e32 v184, v2, v145
	v_bfe_u32 v188, v184, 16, 1
	v_add3_u32 v184, v184, v188, s81
	ds_write_b16_d16_hi v190, v184 offset:7472
	v_mul_f32_e32 v185, v4, v145
	v_bfe_u32 v189, v185, 16, 1
	v_add3_u32 v185, v185, v189, s81
	ds_write_b16_d16_hi v190, v185 offset:7536
	s_or_b32 s0, s40, s99
	s_mov_b32 s1, s41
	s_lshl_b64 s[0:1], s[0:1], 11
	v_lshlrev_b32_e32 v0, 1, v169
	v_lshrrev_b32_e32 v6, 4, v168
	v_and_b32_e32 v96, 0xf0, v0
	v_mul_u32_u24_e32 v0, 0x110, v6
	s_add_u32 s0, s92, s0
	v_add3_u32 v8, s34, v96, v0
	s_addc_u32 s1, s93, s1
	s_lshl_b32 s35, s98, 8
	s_add_u32 s0, s0, s35
	s_addc_u32 s1, s1, 0
	s_waitcnt lgkmcnt(0)
	ds_read_b128 v[132:135], v8
	ds_read_b128 v[136:139], v8 offset:1088
	ds_read_b128 v[140:143], v8 offset:2176
	ds_read_b128 v[144:147], v8 offset:3264
	ds_read_b128 v[148:151], v8 offset:4352
	ds_read_b128 v[172:175], v8 offset:5440
	ds_read_b128 v[176:179], v8 offset:6528
	ds_read_b128 v[180:183], v8 offset:7616
	v_lshl_add_u64 v[4:5], s[0:1], 0, v[96:97]
	v_lshlrev_b32_e32 v96, 11, v6
	v_lshl_add_u64 v[6:7], v[4:5], 0, v[96:97]
	s_waitcnt lgkmcnt(7)
	global_store_dwordx4 v[6:7], v[132:135], off sc1 nt
	v_or_b32_e32 v6, 0x2000, v96
	v_mov_b32_e32 v7, v97
	v_lshl_add_u64 v[6:7], v[4:5], 0, v[6:7]
	s_waitcnt lgkmcnt(6)
	global_store_dwordx4 v[6:7], v[136:139], off sc1 nt
	v_or_b32_e32 v6, 0x4000, v96
	v_mov_b32_e32 v7, v97
	v_lshl_add_u64 v[6:7], v[4:5], 0, v[6:7]
	s_waitcnt lgkmcnt(5)
	global_store_dwordx4 v[6:7], v[140:143], off sc1 nt
	v_or_b32_e32 v6, 0x6000, v96
	v_mov_b32_e32 v7, v97
	v_lshl_add_u64 v[6:7], v[4:5], 0, v[6:7]
	s_waitcnt lgkmcnt(4)
	global_store_dwordx4 v[6:7], v[144:147], off sc1 nt
	v_or_b32_e32 v6, 0x8000, v96
	v_mov_b32_e32 v7, v97
	v_lshl_add_u64 v[6:7], v[4:5], 0, v[6:7]
	s_waitcnt lgkmcnt(3)
	global_store_dwordx4 v[6:7], v[148:151], off sc1 nt
	v_or_b32_e32 v6, 0xa000, v96
	v_mov_b32_e32 v7, v97
	v_lshl_add_u64 v[6:7], v[4:5], 0, v[6:7]
	s_waitcnt lgkmcnt(2)
	global_store_dwordx4 v[6:7], v[172:175], off sc1 nt
	v_or_b32_e32 v6, 0xc000, v96
	v_mov_b32_e32 v7, v97
	v_lshl_add_u64 v[6:7], v[4:5], 0, v[6:7]
	s_waitcnt lgkmcnt(1)
	global_store_dwordx4 v[6:7], v[176:179], off sc1 nt
	v_or_b32_e32 v96, 0xe000, v96
	v_lshl_add_u64 v[4:5], v[4:5], 0, v[96:97]
	s_waitcnt lgkmcnt(0)
	global_store_dwordx4 v[4:5], v[180:183], off sc1 nt
	s_branch .LBB0_275
